# non-temporal (nt) stores for write-once f32 k/v cache outputs and gate buffer in the input projection epilogue
# speedup vs baseline: 1.1363x; 1.0022x over previous
; __device__ void phase_inproj(const Params& p, char* lds) {
;     ...
;         const int tok = m0 + wr * 64 + i * 32 + l31; const int cb = n0 + wc * 64 + j * 32;
;         if (nt < 8) {
;           st_bf16_sw((bf16_t*)(ws + W_C) + (size_t)tok * LDH + cb, acc[i][j], hh, 0.125f * LOG2E);
;         } else if (nt < 16) {
;           st_f32_sw((samp ? p.out + O_KS + (size_t)(tok - TP) * 1024 : p.out + O_KP + (size_t)tok * 1024) + (cb - 1024), acc[i][j], hh);
;           st_bf16_sw((bf16_t*)(ws + W_D) + (size_t)keyrow_of_token(tok) * LDH + (cb - 1024), acc[i][j], hh, 1.f);
;         } else if (nt < 26) {
;           st_f32_sw((float*)(ws + F_ZCQ) + (size_t)tok * 256 + (cb - 3072), acc[i][j], hh);
;         } else if (nt == 26) {
;           st_f32_sw((float*)(ws + F_ZCKV) + (size_t)tok * 128 + (cb - 3328), acc[i][j], hh);
;         } else if (nt == 27) {
;           if (cb == 3456) st_f32_sw((float*)(ws + F_ZKR) + (size_t)tok * 32, acc[i][j], hh);
;         } else {
;           f32x16 sg;
; #pragma unroll
;           for (int r = 0; r < 16; ++r) sg[r] = __builtin_amdgcn_rcpf(1.f + __expf(-acc[i][j][r]));
;           st_bf16_sw((bf16_t*)(p.out + O_Y) + (size_t)tok * 2048 + (cb - 3584), sg, hh, 1.f);
.LBB0_180:
	s_cmp_eq_u32 s51, 27
	s_cbranch_scc1 .Lp1_old
	v_and_b32_e32 v165, 63, v181
	v_lshrrev_b32_e32 v164, 6, v181
	v_and_b32_e32 v138, 31, v165
	v_lshrrev_b32_e32 v139, 5, v165
	v_mul_u32_u24_e32 v138, 0x110, v138
	v_lshlrev_b32_e32 v139, 4, v139
	v_mul_u32_u24_e32 v140, 0x2200, v164
	v_add3_u32 v138, v138, v139, v140
	v_add_u32_e32 v138, 0x8000, v138
	v_add_u32_e32 v139, 0x8000, v140
	v_lshrrev_b32_e32 v140, 3, v165
	v_and_b32_e32 v141, 7, v165
	v_mul_u32_u24_e32 v165, 0x110, v140
	v_add_u32_e32 v139, v139, v165
	v_lshl_add_u32 v139, v141, 5, v139
	s_cmp_lt_u32 s51, 8
	s_cbranch_scc1 .Lp1_q
	s_cmp_lt_u32 s51, 16
	s_cbranch_scc1 .Lp1_k
	s_cmp_lt_u32 s51, 26
	s_cbranch_scc1 .Lp1_zcq
	s_cmp_eq_u32 s51, 26
	s_cbranch_scc1 .Lp1_zckv
	v_mul_f32_e32 v48, 0xbfb8aa3b, v48
	v_mul_f32_e32 v49, 0xbfb8aa3b, v49
	v_mul_f32_e32 v50, 0xbfb8aa3b, v50
	v_mul_f32_e32 v51, 0xbfb8aa3b, v51
	v_exp_f32_e32 v48, v48
	v_exp_f32_e32 v49, v49
	v_exp_f32_e32 v50, v50
	v_exp_f32_e32 v51, v51
	v_add_f32_e32 v48, 1.0, v48
	v_add_f32_e32 v49, 1.0, v49
	v_add_f32_e32 v50, 1.0, v50
	v_add_f32_e32 v51, 1.0, v51
	v_rcp_f32_e32 v48, v48
	v_rcp_f32_e32 v49, v49
	v_rcp_f32_e32 v50, v50
	v_rcp_f32_e32 v51, v51
	v_mul_f32_e32 v52, 0xbfb8aa3b, v52
	v_mul_f32_e32 v53, 0xbfb8aa3b, v53
	v_mul_f32_e32 v54, 0xbfb8aa3b, v54
	v_mul_f32_e32 v55, 0xbfb8aa3b, v55
	v_exp_f32_e32 v52, v52
	v_exp_f32_e32 v53, v53
	v_exp_f32_e32 v54, v54
	v_exp_f32_e32 v55, v55
	v_add_f32_e32 v52, 1.0, v52
	v_add_f32_e32 v53, 1.0, v53
	v_add_f32_e32 v54, 1.0, v54
	v_add_f32_e32 v55, 1.0, v55
	v_rcp_f32_e32 v52, v52
	v_rcp_f32_e32 v53, v53
	v_rcp_f32_e32 v54, v54
	v_rcp_f32_e32 v55, v55
	v_mul_f32_e32 v56, 0xbfb8aa3b, v56
	v_mul_f32_e32 v57, 0xbfb8aa3b, v57
	v_mul_f32_e32 v58, 0xbfb8aa3b, v58
	v_mul_f32_e32 v59, 0xbfb8aa3b, v59
	v_exp_f32_e32 v56, v56
	v_exp_f32_e32 v57, v57
	v_exp_f32_e32 v58, v58
	v_exp_f32_e32 v59, v59
	v_add_f32_e32 v56, 1.0, v56
	v_add_f32_e32 v57, 1.0, v57
	v_add_f32_e32 v58, 1.0, v58
	v_add_f32_e32 v59, 1.0, v59
	v_rcp_f32_e32 v56, v56
	v_rcp_f32_e32 v57, v57
	v_rcp_f32_e32 v58, v58
	v_rcp_f32_e32 v59, v59
	v_mul_f32_e32 v60, 0xbfb8aa3b, v60
	v_mul_f32_e32 v61, 0xbfb8aa3b, v61
	v_mul_f32_e32 v62, 0xbfb8aa3b, v62
	v_mul_f32_e32 v63, 0xbfb8aa3b, v63
	v_exp_f32_e32 v60, v60
	v_exp_f32_e32 v61, v61
	v_exp_f32_e32 v62, v62
	v_exp_f32_e32 v63, v63
	v_add_f32_e32 v60, 1.0, v60
	v_add_f32_e32 v61, 1.0, v61
	v_add_f32_e32 v62, 1.0, v62
	v_add_f32_e32 v63, 1.0, v63
	v_rcp_f32_e32 v60, v60
	v_rcp_f32_e32 v61, v61
	v_rcp_f32_e32 v62, v62
	v_rcp_f32_e32 v63, v63
	v_mul_f32_e32 v32, 0xbfb8aa3b, v32
	v_mul_f32_e32 v33, 0xbfb8aa3b, v33
	v_mul_f32_e32 v34, 0xbfb8aa3b, v34
	v_mul_f32_e32 v35, 0xbfb8aa3b, v35
	v_exp_f32_e32 v32, v32
	v_exp_f32_e32 v33, v33
	v_exp_f32_e32 v34, v34
	v_exp_f32_e32 v35, v35
	v_add_f32_e32 v32, 1.0, v32
	v_add_f32_e32 v33, 1.0, v33
	v_add_f32_e32 v34, 1.0, v34
	v_add_f32_e32 v35, 1.0, v35
	v_rcp_f32_e32 v32, v32
	v_rcp_f32_e32 v33, v33
	v_rcp_f32_e32 v34, v34
	v_rcp_f32_e32 v35, v35
	v_mul_f32_e32 v36, 0xbfb8aa3b, v36
	v_mul_f32_e32 v37, 0xbfb8aa3b, v37
	v_mul_f32_e32 v38, 0xbfb8aa3b, v38
	v_mul_f32_e32 v39, 0xbfb8aa3b, v39
	v_exp_f32_e32 v36, v36
	v_exp_f32_e32 v37, v37
	v_exp_f32_e32 v38, v38
	v_exp_f32_e32 v39, v39
	v_add_f32_e32 v36, 1.0, v36
	v_add_f32_e32 v37, 1.0, v37
	v_add_f32_e32 v38, 1.0, v38
	v_add_f32_e32 v39, 1.0, v39
	v_rcp_f32_e32 v36, v36
	v_rcp_f32_e32 v37, v37
	v_rcp_f32_e32 v38, v38
	v_rcp_f32_e32 v39, v39
	v_mul_f32_e32 v40, 0xbfb8aa3b, v40
	v_mul_f32_e32 v41, 0xbfb8aa3b, v41
	v_mul_f32_e32 v42, 0xbfb8aa3b, v42
	v_mul_f32_e32 v43, 0xbfb8aa3b, v43
	v_exp_f32_e32 v40, v40
	v_exp_f32_e32 v41, v41
	v_exp_f32_e32 v42, v42
	v_exp_f32_e32 v43, v43
	v_add_f32_e32 v40, 1.0, v40
	v_add_f32_e32 v41, 1.0, v41
	v_add_f32_e32 v42, 1.0, v42
	v_add_f32_e32 v43, 1.0, v43
	v_rcp_f32_e32 v40, v40
	v_rcp_f32_e32 v41, v41
	v_rcp_f32_e32 v42, v42
	v_rcp_f32_e32 v43, v43
	v_mul_f32_e32 v44, 0xbfb8aa3b, v44
	v_mul_f32_e32 v45, 0xbfb8aa3b, v45
	v_mul_f32_e32 v46, 0xbfb8aa3b, v46
	v_mul_f32_e32 v47, 0xbfb8aa3b, v47
	v_exp_f32_e32 v44, v44
	v_exp_f32_e32 v45, v45
	v_exp_f32_e32 v46, v46
	v_exp_f32_e32 v47, v47
	v_add_f32_e32 v44, 1.0, v44
	v_add_f32_e32 v45, 1.0, v45
	v_add_f32_e32 v46, 1.0, v46
	v_add_f32_e32 v47, 1.0, v47
	v_rcp_f32_e32 v44, v44
	v_rcp_f32_e32 v45, v45
	v_rcp_f32_e32 v46, v46
	v_rcp_f32_e32 v47, v47
	v_mul_f32_e32 v16, 0xbfb8aa3b, v16
	v_mul_f32_e32 v17, 0xbfb8aa3b, v17
	v_mul_f32_e32 v18, 0xbfb8aa3b, v18
	v_mul_f32_e32 v19, 0xbfb8aa3b, v19
	v_exp_f32_e32 v16, v16
	v_exp_f32_e32 v17, v17
	v_exp_f32_e32 v18, v18
	v_exp_f32_e32 v19, v19
	v_add_f32_e32 v16, 1.0, v16
	v_add_f32_e32 v17, 1.0, v17
	v_add_f32_e32 v18, 1.0, v18
	v_add_f32_e32 v19, 1.0, v19
	v_rcp_f32_e32 v16, v16
	v_rcp_f32_e32 v17, v17
	v_rcp_f32_e32 v18, v18
	v_rcp_f32_e32 v19, v19
	v_mul_f32_e32 v20, 0xbfb8aa3b, v20
	v_mul_f32_e32 v21, 0xbfb8aa3b, v21
	v_mul_f32_e32 v22, 0xbfb8aa3b, v22
	v_mul_f32_e32 v23, 0xbfb8aa3b, v23
	v_exp_f32_e32 v20, v20
	v_exp_f32_e32 v21, v21
	v_exp_f32_e32 v22, v22
	v_exp_f32_e32 v23, v23
	v_add_f32_e32 v20, 1.0, v20
	v_add_f32_e32 v21, 1.0, v21
	v_add_f32_e32 v22, 1.0, v22
	v_add_f32_e32 v23, 1.0, v23
	v_rcp_f32_e32 v20, v20
	v_rcp_f32_e32 v21, v21
	v_rcp_f32_e32 v22, v22
	v_rcp_f32_e32 v23, v23
	v_mul_f32_e32 v24, 0xbfb8aa3b, v24
	v_mul_f32_e32 v25, 0xbfb8aa3b, v25
	v_mul_f32_e32 v26, 0xbfb8aa3b, v26
	v_mul_f32_e32 v27, 0xbfb8aa3b, v27
	v_exp_f32_e32 v24, v24
	v_exp_f32_e32 v25, v25
	v_exp_f32_e32 v26, v26
	v_exp_f32_e32 v27, v27
	v_add_f32_e32 v24, 1.0, v24
	v_add_f32_e32 v25, 1.0, v25
	v_add_f32_e32 v26, 1.0, v26
	v_add_f32_e32 v27, 1.0, v27
	v_rcp_f32_e32 v24, v24
; __device__ __forceinline__ unsigned pk2(float lo, float hi) { f32v2_t v = {lo, hi}; bf16v2_t r = __builtin_convertvector(v, bf16v2_t); return __builtin_bit_cast(unsigned, r); }
; __device__ __forceinline__ void st_bf16_sw(bf16_t* row, const f32x16& a, int hh, float sc) {
; #pragma unroll
;   for (int g = 0; g < 4; ++g) { u32x2 w; w.x = pk2(a[4 * g] * sc, a[4 * g + 1] * sc); w.y = pk2(a[4 * g + 2] * sc, a[4 * g + 3] * sc); *(u32x2*)(row + 8 * g + 4 * hh) = w; }
; }
; __device__ void phase_inproj(const Params& p, char* lds) {
;     ...
;         } else {
;           f32x16 sg;
; #pragma unroll
;           for (int r = 0; r < 16; ++r) sg[r] = __builtin_amdgcn_rcpf(1.f + __expf(-acc[i][j][r]));
;           st_bf16_sw((bf16_t*)(p.out + O_Y) + (size_t)tok * 2048 + (cb - 3584), sg, hh, 1.f);
	v_rcp_f32_e32 v25, v25
	v_rcp_f32_e32 v26, v26
	v_rcp_f32_e32 v27, v27
	v_mul_f32_e32 v28, 0xbfb8aa3b, v28
	v_mul_f32_e32 v29, 0xbfb8aa3b, v29
	v_mul_f32_e32 v30, 0xbfb8aa3b, v30
	v_mul_f32_e32 v31, 0xbfb8aa3b, v31
	v_exp_f32_e32 v28, v28
	v_exp_f32_e32 v29, v29
	v_exp_f32_e32 v30, v30
	v_exp_f32_e32 v31, v31
	v_add_f32_e32 v28, 1.0, v28
	v_add_f32_e32 v29, 1.0, v29
	v_add_f32_e32 v30, 1.0, v30
	v_add_f32_e32 v31, 1.0, v31
	v_rcp_f32_e32 v28, v28
	v_rcp_f32_e32 v29, v29
	v_rcp_f32_e32 v30, v30
	v_rcp_f32_e32 v31, v31
	v_mul_f32_e32 v0, 0xbfb8aa3b, v0
	v_mul_f32_e32 v1, 0xbfb8aa3b, v1
	v_mul_f32_e32 v2, 0xbfb8aa3b, v2
	v_mul_f32_e32 v3, 0xbfb8aa3b, v3
	v_exp_f32_e32 v0, v0
	v_exp_f32_e32 v1, v1
	v_exp_f32_e32 v2, v2
	v_exp_f32_e32 v3, v3
	v_add_f32_e32 v0, 1.0, v0
	v_add_f32_e32 v1, 1.0, v1
	v_add_f32_e32 v2, 1.0, v2
	v_add_f32_e32 v3, 1.0, v3
	v_rcp_f32_e32 v0, v0
	v_rcp_f32_e32 v1, v1
	v_rcp_f32_e32 v2, v2
	v_rcp_f32_e32 v3, v3
	v_mul_f32_e32 v4, 0xbfb8aa3b, v4
	v_mul_f32_e32 v5, 0xbfb8aa3b, v5
	v_mul_f32_e32 v6, 0xbfb8aa3b, v6
	v_mul_f32_e32 v7, 0xbfb8aa3b, v7
	v_exp_f32_e32 v4, v4
	v_exp_f32_e32 v5, v5
	v_exp_f32_e32 v6, v6
	v_exp_f32_e32 v7, v7
	v_add_f32_e32 v4, 1.0, v4
	v_add_f32_e32 v5, 1.0, v5
	v_add_f32_e32 v6, 1.0, v6
	v_add_f32_e32 v7, 1.0, v7
	v_rcp_f32_e32 v4, v4
	v_rcp_f32_e32 v5, v5
	v_rcp_f32_e32 v6, v6
	v_rcp_f32_e32 v7, v7
	v_mul_f32_e32 v8, 0xbfb8aa3b, v8
	v_mul_f32_e32 v9, 0xbfb8aa3b, v9
	v_mul_f32_e32 v10, 0xbfb8aa3b, v10
	v_mul_f32_e32 v11, 0xbfb8aa3b, v11
	v_exp_f32_e32 v8, v8
	v_exp_f32_e32 v9, v9
	v_exp_f32_e32 v10, v10
	v_exp_f32_e32 v11, v11
	v_add_f32_e32 v8, 1.0, v8
	v_add_f32_e32 v9, 1.0, v9
	v_add_f32_e32 v10, 1.0, v10
	v_add_f32_e32 v11, 1.0, v11
	v_rcp_f32_e32 v8, v8
	v_rcp_f32_e32 v9, v9
	v_rcp_f32_e32 v10, v10
	v_rcp_f32_e32 v11, v11
	v_mul_f32_e32 v12, 0xbfb8aa3b, v12
	v_mul_f32_e32 v13, 0xbfb8aa3b, v13
	v_mul_f32_e32 v14, 0xbfb8aa3b, v14
	v_mul_f32_e32 v15, 0xbfb8aa3b, v15
	v_exp_f32_e32 v12, v12
	v_exp_f32_e32 v13, v13
	v_exp_f32_e32 v14, v14
	v_exp_f32_e32 v15, v15
	v_add_f32_e32 v12, 1.0, v12
	v_add_f32_e32 v13, 1.0, v13
	v_add_f32_e32 v14, 1.0, v14
	v_add_f32_e32 v15, 1.0, v15
	v_rcp_f32_e32 v12, v12
	v_rcp_f32_e32 v13, v13
	v_rcp_f32_e32 v14, v14
	v_rcp_f32_e32 v15, v15
	v_readlane_b32 s2, v248, 4
	v_readlane_b32 s3, v248, 5
	s_lshl_b32 s0, s53, 12
	s_sub_i32 s1, s54, 0xe00
	s_lshl_b32 s1, s1, 1
	s_add_i32 s0, s0, s1
	v_lshrrev_b32_e32 v169, 1, v164
	v_mul_u32_u24_e32 v169, 0x40000, v169
	v_mul_u32_u24_e32 v171, 0x1000, v140
	v_add_u32_e32 v169, v169, v171
	v_and_b32_e32 v171, 1, v164
	v_mul_u32_u24_e32 v171, 0x80, v171
	v_lshl_add_u32 v171, v141, 4, v171
	v_add3_u32 v169, v169, v171, s0
	ds_write_b128 v138, v[48:51] offset:0
	ds_write_b128 v138, v[52:55] offset:32
	ds_write_b128 v138, v[56:59] offset:64
	ds_write_b128 v138, v[60:63] offset:96
	ds_write_b128 v138, v[32:35] offset:128
	ds_write_b128 v138, v[36:39] offset:160
	ds_write_b128 v138, v[40:43] offset:192
	ds_write_b128 v138, v[44:47] offset:224
	s_waitcnt lgkmcnt(0)
	ds_read_b128 v[32:35], v139 offset:0
	ds_read_b128 v[36:39], v139 offset:16
	ds_read_b128 v[40:43], v139 offset:2176
	ds_read_b128 v[44:47], v139 offset:2192
	ds_read_b128 v[48:51], v139 offset:4352
	ds_read_b128 v[52:55], v139 offset:4368
	ds_read_b128 v[56:59], v139 offset:6528
	ds_read_b128 v[60:63], v139 offset:6544
	s_waitcnt lgkmcnt(6)
	v_cvt_pk_bf16_f32 v32, v32, v33
	v_cvt_pk_bf16_f32 v33, v34, v35
	v_cvt_pk_bf16_f32 v34, v36, v37
	v_cvt_pk_bf16_f32 v35, v38, v39
	global_store_dwordx4 v169, v[32:35], s[2:3] nt
	v_add_u32_e32 v169, 0x8000, v169
	s_waitcnt lgkmcnt(4)
	v_cvt_pk_bf16_f32 v40, v40, v41
	v_cvt_pk_bf16_f32 v41, v42, v43
	v_cvt_pk_bf16_f32 v42, v44, v45
	v_cvt_pk_bf16_f32 v43, v46, v47
	global_store_dwordx4 v169, v[40:43], s[2:3] nt
	v_add_u32_e32 v169, 0x8000, v169
	s_waitcnt lgkmcnt(2)
	v_cvt_pk_bf16_f32 v48, v48, v49
	v_cvt_pk_bf16_f32 v49, v50, v51
	v_cvt_pk_bf16_f32 v50, v52, v53
	v_cvt_pk_bf16_f32 v51, v54, v55
	global_store_dwordx4 v169, v[48:51], s[2:3] nt
	v_add_u32_e32 v169, 0x8000, v169
	s_waitcnt lgkmcnt(0)
	v_cvt_pk_bf16_f32 v56, v56, v57
	v_cvt_pk_bf16_f32 v57, v58, v59
	v_cvt_pk_bf16_f32 v58, v60, v61
	v_cvt_pk_bf16_f32 v59, v62, v63
	global_store_dwordx4 v169, v[56:59], s[2:3] nt
	v_add_u32_e32 v169, 0x8000, v169
	ds_write_b128 v138, v[16:19] offset:0
	ds_write_b128 v138, v[20:23] offset:32
	ds_write_b128 v138, v[24:27] offset:64
	ds_write_b128 v138, v[28:31] offset:96
	ds_write_b128 v138, v[0:3] offset:128
	ds_write_b128 v138, v[4:7] offset:160
	ds_write_b128 v138, v[8:11] offset:192
	ds_write_b128 v138, v[12:15] offset:224
	s_waitcnt lgkmcnt(0)
	ds_read_b128 v[0:3], v139 offset:0
	ds_read_b128 v[4:7], v139 offset:16
	ds_read_b128 v[8:11], v139 offset:2176
	ds_read_b128 v[12:15], v139 offset:2192
	ds_read_b128 v[16:19], v139 offset:4352
	ds_read_b128 v[20:23], v139 offset:4368
	ds_read_b128 v[24:27], v139 offset:6528
	ds_read_b128 v[28:31], v139 offset:6544
	s_waitcnt lgkmcnt(6)
	v_cvt_pk_bf16_f32 v0, v0, v1
	v_cvt_pk_bf16_f32 v1, v2, v3
	v_cvt_pk_bf16_f32 v2, v4, v5
	v_cvt_pk_bf16_f32 v3, v6, v7
	global_store_dwordx4 v169, v[0:3], s[2:3] nt
	v_add_u32_e32 v169, 0x8000, v169
	s_waitcnt lgkmcnt(4)
	v_cvt_pk_bf16_f32 v8, v8, v9
	v_cvt_pk_bf16_f32 v9, v10, v11
	v_cvt_pk_bf16_f32 v10, v12, v13
	v_cvt_pk_bf16_f32 v11, v14, v15
	global_store_dwordx4 v169, v[8:11], s[2:3] nt
	v_add_u32_e32 v169, 0x8000, v169
	s_waitcnt lgkmcnt(2)
	v_cvt_pk_bf16_f32 v16, v16, v17
	v_cvt_pk_bf16_f32 v17, v18, v19
	v_cvt_pk_bf16_f32 v18, v20, v21
	v_cvt_pk_bf16_f32 v19, v22, v23
	global_store_dwordx4 v169, v[16:19], s[2:3] nt
	v_add_u32_e32 v169, 0x8000, v169
	s_waitcnt lgkmcnt(0)
	v_cvt_pk_bf16_f32 v24, v24, v25
	v_cvt_pk_bf16_f32 v25, v26, v27
	v_cvt_pk_bf16_f32 v26, v28, v29
	v_cvt_pk_bf16_f32 v27, v30, v31
	global_store_dwordx4 v169, v[24:27], s[2:3] nt
	v_add_u32_e32 v169, 0x8000, v169
	s_branch .LBB0_260

; __device__ __forceinline__ unsigned pk2(float lo, float hi) { f32v2_t v = {lo, hi}; bf16v2_t r = __builtin_convertvector(v, bf16v2_t); return __builtin_bit_cast(unsigned, r); }
; __device__ __forceinline__ void st_bf16_sw(bf16_t* row, const f32x16& a, int hh, float sc) {
; #pragma unroll
;   for (int g = 0; g < 4; ++g) { u32x2 w; w.x = pk2(a[4 * g] * sc, a[4 * g + 1] * sc); w.y = pk2(a[4 * g + 2] * sc, a[4 * g + 3] * sc); *(u32x2*)(row + 8 * g + 4 * hh) = w; }
; }
; __device__ __forceinline__ void st_f32_sw(float* row, const f32x16& a, int hh) {
; #pragma unroll
;   for (int g = 0; g < 4; ++g) { f32x4 w = {a[4 * g], a[4 * g + 1], a[4 * g + 2], a[4 * g + 3]}; *(f32x4*)(row + 8 * g + 4 * hh) = w; }
; }
; __device__ void phase_inproj(const Params& p, char* lds) {
;     ...
;         } else if (nt < 16) {
;           st_f32_sw((samp ? p.out + O_KS + (size_t)(tok - TP) * 1024 : p.out + O_KP + (size_t)tok * 1024) + (cb - 1024), acc[i][j], hh);
;           st_bf16_sw((bf16_t*)(ws + W_D) + (size_t)keyrow_of_token(tok) * LDH + (cb - 1024), acc[i][j], hh, 1.f);
.Lp1_k_go:
	s_sub_i32 s35, s54, 0x400
	s_lshl_b32 s35, s35, 2
	s_add_i32 s0, s0, s35
	s_lshr_b32 s35, s35, 1
	s_add_i32 s1, s1, s35
	v_lshrrev_b32_e32 v170, 1, v164
	v_mul_u32_u24_e32 v170, 0x40000, v170
	v_mul_u32_u24_e32 v171, 0x1000, v167
	v_add_u32_e32 v170, v170, v171
	v_and_b32_e32 v171, 1, v164
	v_mul_u32_u24_e32 v171, 0x100, v171
	v_lshl_add_u32 v171, v168, 4, v171
	v_add3_u32 v170, v170, v171, s0
	v_lshrrev_b32_e32 v169, 1, v164
	v_mul_lo_u32 v169, v169, s34
	v_mul_u32_u24_e32 v171, 0x880, v140
	v_add_u32_e32 v169, v169, v171
	v_and_b32_e32 v171, 1, v164
	v_mul_u32_u24_e32 v171, 0x80, v171
	v_lshl_add_u32 v171, v141, 4, v171
	v_add3_u32 v169, v169, v171, s1
	ds_write_b128 v138, v[48:51] offset:0
	ds_write_b128 v138, v[52:55] offset:32
	ds_write_b128 v138, v[56:59] offset:64
	ds_write_b128 v138, v[60:63] offset:96
	ds_write_b128 v138, v[32:35] offset:128
	ds_write_b128 v138, v[36:39] offset:160
	ds_write_b128 v138, v[40:43] offset:192
	ds_write_b128 v138, v[44:47] offset:224
	s_waitcnt lgkmcnt(0)
	ds_read_b128 v[32:35], v166 offset:0
	ds_read_b128 v[36:39], v166 offset:1088
	ds_read_b128 v[40:43], v166 offset:2176
	ds_read_b128 v[44:47], v166 offset:3264
	ds_read_b128 v[48:51], v166 offset:4352
	ds_read_b128 v[52:55], v166 offset:5440
	ds_read_b128 v[56:59], v166 offset:6528
	ds_read_b128 v[60:63], v166 offset:7616
	s_waitcnt lgkmcnt(7)
	global_store_dwordx4 v170, v[32:35], s[2:3] nt
	v_add_u32_e32 v170, 0x4000, v170
	s_waitcnt lgkmcnt(6)
	global_store_dwordx4 v170, v[36:39], s[2:3] nt
	v_add_u32_e32 v170, 0x4000, v170
	s_waitcnt lgkmcnt(5)
	global_store_dwordx4 v170, v[40:43], s[2:3] nt
	v_add_u32_e32 v170, 0x4000, v170
	s_waitcnt lgkmcnt(4)
	global_store_dwordx4 v170, v[44:47], s[2:3] nt
	v_add_u32_e32 v170, 0x4000, v170
	s_waitcnt lgkmcnt(3)
	global_store_dwordx4 v170, v[48:51], s[2:3] nt
	v_add_u32_e32 v170, 0x4000, v170
	s_waitcnt lgkmcnt(2)
	global_store_dwordx4 v170, v[52:55], s[2:3] nt
	v_add_u32_e32 v170, 0x4000, v170
	s_waitcnt lgkmcnt(1)
	global_store_dwordx4 v170, v[56:59], s[2:3] nt
	v_add_u32_e32 v170, 0x4000, v170
	s_waitcnt lgkmcnt(0)
	global_store_dwordx4 v170, v[60:63], s[2:3] nt
	v_add_u32_e32 v170, 0x4000, v170
	ds_read_b128 v[32:35], v139 offset:0
	ds_read_b128 v[36:39], v139 offset:16
	ds_read_b128 v[40:43], v139 offset:2176
	ds_read_b128 v[44:47], v139 offset:2192
	ds_read_b128 v[48:51], v139 offset:4352
	ds_read_b128 v[52:55], v139 offset:4368
	ds_read_b128 v[56:59], v139 offset:6528
	ds_read_b128 v[60:63], v139 offset:6544
	s_waitcnt lgkmcnt(6)
	v_cvt_pk_bf16_f32 v32, v32, v33
	v_cvt_pk_bf16_f32 v33, v34, v35
	v_cvt_pk_bf16_f32 v34, v36, v37
	v_cvt_pk_bf16_f32 v35, v38, v39
	global_store_dwordx4 v169, v[32:35], s[96:97]
	v_add_u32_e32 v169, 0x4400, v169
	s_waitcnt lgkmcnt(4)
	v_cvt_pk_bf16_f32 v40, v40, v41
	v_cvt_pk_bf16_f32 v41, v42, v43
	v_cvt_pk_bf16_f32 v42, v44, v45
	v_cvt_pk_bf16_f32 v43, v46, v47
	global_store_dwordx4 v169, v[40:43], s[96:97]
	v_add_u32_e32 v169, 0x4400, v169
	s_waitcnt lgkmcnt(2)
	v_cvt_pk_bf16_f32 v48, v48, v49
	v_cvt_pk_bf16_f32 v49, v50, v51
	v_cvt_pk_bf16_f32 v50, v52, v53
	v_cvt_pk_bf16_f32 v51, v54, v55
	global_store_dwordx4 v169, v[48:51], s[96:97]
	v_add_u32_e32 v169, 0x4400, v169
	s_waitcnt lgkmcnt(0)
	v_cvt_pk_bf16_f32 v56, v56, v57
	v_cvt_pk_bf16_f32 v57, v58, v59
	v_cvt_pk_bf16_f32 v58, v60, v61
	v_cvt_pk_bf16_f32 v59, v62, v63
	global_store_dwordx4 v169, v[56:59], s[96:97]
	v_add_u32_e32 v169, 0x4400, v169
	ds_write_b128 v138, v[16:19] offset:0
	ds_write_b128 v138, v[20:23] offset:32
	ds_write_b128 v138, v[24:27] offset:64
	ds_write_b128 v138, v[28:31] offset:96
	ds_write_b128 v138, v[0:3] offset:128
	ds_write_b128 v138, v[4:7] offset:160
	ds_write_b128 v138, v[8:11] offset:192
	ds_write_b128 v138, v[12:15] offset:224
	s_waitcnt lgkmcnt(0)
	ds_read_b128 v[0:3], v166 offset:0
	ds_read_b128 v[4:7], v166 offset:1088
	ds_read_b128 v[8:11], v166 offset:2176
	ds_read_b128 v[12:15], v166 offset:3264
	ds_read_b128 v[16:19], v166 offset:4352
	ds_read_b128 v[20:23], v166 offset:5440
	ds_read_b128 v[24:27], v166 offset:6528
	ds_read_b128 v[28:31], v166 offset:7616
	s_waitcnt lgkmcnt(7)
	global_store_dwordx4 v170, v[0:3], s[2:3] nt
	v_add_u32_e32 v170, 0x4000, v170
	s_waitcnt lgkmcnt(6)
	global_store_dwordx4 v170, v[4:7], s[2:3] nt
	v_add_u32_e32 v170, 0x4000, v170
	s_waitcnt lgkmcnt(5)
	global_store_dwordx4 v170, v[8:11], s[2:3] nt
	v_add_u32_e32 v170, 0x4000, v170
	s_waitcnt lgkmcnt(4)
	global_store_dwordx4 v170, v[12:15], s[2:3] nt
	v_add_u32_e32 v170, 0x4000, v170
	s_waitcnt lgkmcnt(3)
	global_store_dwordx4 v170, v[16:19], s[2:3] nt
	v_add_u32_e32 v170, 0x4000, v170
	s_waitcnt lgkmcnt(2)
	global_store_dwordx4 v170, v[20:23], s[2:3] nt
	v_add_u32_e32 v170, 0x4000, v170
	s_waitcnt lgkmcnt(1)
	global_store_dwordx4 v170, v[24:27], s[2:3] nt
	v_add_u32_e32 v170, 0x4000, v170
	s_waitcnt lgkmcnt(0)
	global_store_dwordx4 v170, v[28:31], s[2:3] nt
	v_add_u32_e32 v170, 0x4000, v170
	ds_read_b128 v[0:3], v139 offset:0
	ds_read_b128 v[4:7], v139 offset:16
	ds_read_b128 v[8:11], v139 offset:2176
	ds_read_b128 v[12:15], v139 offset:2192
	ds_read_b128 v[16:19], v139 offset:4352
	ds_read_b128 v[20:23], v139 offset:4368
	ds_read_b128 v[24:27], v139 offset:6528
	ds_read_b128 v[28:31], v139 offset:6544
	s_waitcnt lgkmcnt(6)
	v_cvt_pk_bf16_f32 v0, v0, v1
	v_cvt_pk_bf16_f32 v1, v2, v3
	v_cvt_pk_bf16_f32 v2, v4, v5
	v_cvt_pk_bf16_f32 v3, v6, v7
	global_store_dwordx4 v169, v[0:3], s[96:97]
	v_add_u32_e32 v169, 0x4400, v169
	s_waitcnt lgkmcnt(4)
	v_cvt_pk_bf16_f32 v8, v8, v9
	v_cvt_pk_bf16_f32 v9, v10, v11
	v_cvt_pk_bf16_f32 v10, v12, v13
	v_cvt_pk_bf16_f32 v11, v14, v15
	global_store_dwordx4 v169, v[8:11], s[96:97]
	v_add_u32_e32 v169, 0x4400, v169
	s_waitcnt lgkmcnt(2)
	v_cvt_pk_bf16_f32 v16, v16, v17
	v_cvt_pk_bf16_f32 v17, v18, v19
	v_cvt_pk_bf16_f32 v18, v20, v21
	v_cvt_pk_bf16_f32 v19, v22, v23
	global_store_dwordx4 v169, v[16:19], s[96:97]
	v_add_u32_e32 v169, 0x4400, v169
	s_waitcnt lgkmcnt(0)
	v_cvt_pk_bf16_f32 v24, v24, v25
	v_cvt_pk_bf16_f32 v25, v26, v27
	v_cvt_pk_bf16_f32 v26, v28, v29
	v_cvt_pk_bf16_f32 v27, v30, v31
	global_store_dwordx4 v169, v[24:27], s[96:97]
	v_add_u32_e32 v169, 0x4400, v169
	s_branch .LBB0_260

; __device__ __forceinline__ unsigned pk2(float lo, float hi) { f32v2_t v = {lo, hi}; bf16v2_t r = __builtin_convertvector(v, bf16v2_t); return __builtin_bit_cast(unsigned, r); }
; __device__ __forceinline__ int accrow(int reg, int hh) { return (reg & 3) + 8 * (reg >> 2) + 4 * hh; }
; __device__ __forceinline__ void vt_store(bf16_t* vt_row, int key32, const f32x16& a, int hh) {
; #pragma unroll
;   for (int g = 0; g < 4; ++g) {
;     const int pos = key32 + (g >> 1) * 16 + hh * 8 + (g & 1) * 4;
;     u32x2 w; w.x = pk2(a[4 * g], a[4 * g + 1]); w.y = pk2(a[4 * g + 2], a[4 * g + 3]);
;     *(u32x2*)(vt_row + pos) = w;
;   }
; }
; __device__ void phase_inproj(const Params& p, char* lds) {
;     ...
;           const int mb = m0 + wr * 64 + i * 32; const int nn = n0 - 2048 + wc * 64 + j * 32 + l31;
;           float* o = (samp ? p.out + O_VS + (size_t)(mb - TP) * 1024 : p.out + O_VP + (size_t)mb * 1024) + nn;
; #pragma unroll
;           for (int r = 0; r < 16; ++r) o[(size_t)accrow(r, hh) * 1024] = acc[i][j][r];
;           bf16_t* vt; int key32;
;           if (!samp) { const int b = mb >> 12; vt = (bf16_t*)(ws + W_D2) + ((size_t)(b * 1024 + nn)) * SEQP; key32 = mb & 4095; }
;           else { const int ts = mb - TP; const int b = ts >> 6; vt = (bf16_t*)(ws + W_D2 + SZ_VTP) + ((size_t)(b * 1024 + nn)) * LKS; key32 = PAST + (ts & 63); }
;           vt_store(vt, key32, acc[i][j], hh);
.LBB0_268:
	v_readlane_b32 s2, v248, 0
	v_readlane_b32 s3, v248, 1
	s_load_dwordx4 s[40:43], s[2:3], 0xc0
	v_add_u32_e32 v118, s53, v148
	s_and_b64 s[0:1], s[38:39], exec
	v_ashrrev_i32_e32 v119, 31, v118
	s_mov_b32 s0, 0x19800000
	v_lshlrev_b64 v[120:121], 12, v[118:119]
	s_cselect_b32 s0, s0, 0x10200000
	v_lshl_add_u64 v[122:123], v[120:121], 0, s[24:25]
	s_waitcnt lgkmcnt(0)
	s_add_u32 s0, s42, s0
	v_cndmask_b32_e64 v125, v121, v123, s[38:39]
	v_cndmask_b32_e64 v124, v120, v122, s[38:39]
	s_addc_u32 s1, s43, 0
	v_add_u32_e32 v116, s54, v155
	v_lshl_add_u64 v[124:125], s[0:1], 0, v[124:125]
	v_mov_b32_e32 v117, v65
	v_lshl_add_u64 v[124:125], v[116:117], 2, v[124:125]
	v_lshl_add_u64 v[126:127], v[124:125], 0, v[76:77]
	global_store_dword v[126:127], v48, off nt
	v_lshl_add_u64 v[126:127], v[124:125], 0, v[78:79]
	global_store_dword v[126:127], v49, off nt
	v_lshl_add_u64 v[126:127], v[124:125], 0, v[80:81]
	global_store_dword v[126:127], v50, off nt
	v_lshl_add_u64 v[126:127], v[124:125], 0, v[82:83]
	global_store_dword v[126:127], v51, off nt
	v_lshl_add_u64 v[126:127], v[124:125], 0, v[84:85]
	global_store_dword v[126:127], v52, off nt
	v_lshl_add_u64 v[126:127], v[124:125], 0, v[86:87]
	global_store_dword v[126:127], v53, off nt
	v_lshl_add_u64 v[126:127], v[124:125], 0, v[88:89]
	global_store_dword v[126:127], v54, off nt
	v_lshl_add_u64 v[126:127], v[124:125], 0, v[90:91]
	global_store_dword v[126:127], v55, off nt
	v_lshl_add_u64 v[126:127], v[124:125], 0, v[92:93]
	global_store_dword v[126:127], v56, off nt
	v_lshl_add_u64 v[126:127], v[124:125], 0, v[94:95]
	global_store_dword v[126:127], v57, off nt
	v_lshl_add_u64 v[126:127], v[124:125], 0, v[96:97]
	global_store_dword v[126:127], v58, off nt
	v_lshl_add_u64 v[126:127], v[124:125], 0, v[98:99]
	global_store_dword v[126:127], v59, off nt
	v_lshl_add_u64 v[126:127], v[124:125], 0, v[100:101]
	v_ashrrev_i32_e32 v109, 2, v118
	global_store_dword v[126:127], v60, off nt
	v_lshl_add_u64 v[126:127], v[124:125], 0, v[102:103]
	v_and_b32_e32 v109, 0xfffffc00, v109
	v_and_b32_e32 v113, 0xfc0, v118
	global_store_dword v[126:127], v61, off nt
	v_lshl_add_u64 v[126:127], v[124:125], 0, v[104:105]
	v_lshl_add_u64 v[124:125], v[124:125], 0, v[106:107]
	v_cndmask_b32_e64 v115, 0, 1, s[38:39]
	v_lshl_add_u32 v111, v118, 4, v163
	global_store_dword v[124:125], v63, off nt
	s_mov_b64 s[34:35], 0x1079e000
	s_mov_b64 s[2:3], 0x2080
	s_mov_b64 s[0:1], 0x10200000
	v_cmp_ne_u32_e64 s[40:41], 1, v115
	s_andn2_b64 vcc, exec, s[38:39]
	s_mov_b64 s[42:43], 0x10200000
	v_mov_b32_e32 v124, v109
	s_mov_b64 s[44:45], 0x2080
	s_mov_b64 s[46:47], 0x1079e000
	v_mov_b32_e32 v115, v113
	global_store_dword v[126:127], v62, off nt
	s_cbranch_vccnz .LBB0_270
	v_mov_b32_e32 v115, 0x800
	s_mov_b64 s[46:47], 0x1489e000
	s_mov_b64 s[44:45], 0x1080
	s_mov_b64 s[42:43], 0x19800000
	v_mov_b64_e32 v[120:121], v[122:123]
	v_mov_b32_e32 v124, v111
.LBB0_270:
	s_add_u32 s46, s96, s46
	s_addc_u32 s47, s97, s47
	v_or_b32_e32 v124, v124, v116
	v_mov_b64_e32 v[122:123], s[46:47]
	v_readlane_b32 s48, v248, 0
	v_mad_i64_i32 v[122:123], s[44:45], s44, v124, v[122:123]
	v_readlane_b32 s49, v248, 1
	s_load_dwordx4 s[44:47], s[48:49], 0xc0
	v_or_b32_e32 v115, v115, v186
	v_cvt_pk_bf16_f32 v48, v48, v49
	v_cvt_pk_bf16_f32 v49, v50, v51
	v_lshlrev_b32_e32 v50, 1, v115
	v_mov_b32_e32 v51, v65
	v_lshl_add_u64 v[122:123], v[122:123], 0, v[50:51]
	v_cvt_pk_bf16_f32 v50, v52, v53
	v_cvt_pk_bf16_f32 v51, v54, v55
	s_waitcnt lgkmcnt(0)
	s_add_u32 s42, s46, s42
	global_store_dwordx4 v[122:123], v[48:51], off
	s_addc_u32 s43, s47, s43
	s_and_b64 vcc, exec, s[40:41]
	v_cvt_pk_bf16_f32 v48, v56, v57
	v_cvt_pk_bf16_f32 v49, v58, v59
	v_cvt_pk_bf16_f32 v50, v60, v61
	v_cvt_pk_bf16_f32 v51, v62, v63
	global_store_dwordx4 v[122:123], v[48:51], off offset:32
	s_nop 1
	v_lshl_add_u64 v[48:49], s[42:43], 0, v[120:121]
	v_lshl_add_u64 v[48:49], v[116:117], 2, v[48:49]
	v_lshl_add_u64 v[50:51], v[48:49], 0, s[30:31]
	v_lshl_add_u64 v[48:49], v[48:49], 0, v[76:77]
	global_store_dword v[48:49], v32, off offset:128 nt
	v_lshl_add_u64 v[48:49], v[50:51], 0, v[78:79]
	global_store_dword v[48:49], v33, off nt
	v_lshl_add_u64 v[48:49], v[50:51], 0, v[80:81]
	global_store_dword v[48:49], v34, off nt
	v_lshl_add_u64 v[48:49], v[50:51], 0, v[82:83]
	global_store_dword v[48:49], v35, off nt
	v_lshl_add_u64 v[48:49], v[50:51], 0, v[84:85]
	global_store_dword v[48:49], v36, off nt
	v_lshl_add_u64 v[48:49], v[50:51], 0, v[86:87]
	global_store_dword v[48:49], v37, off nt
	v_lshl_add_u64 v[48:49], v[50:51], 0, v[88:89]
	global_store_dword v[48:49], v38, off nt
	v_lshl_add_u64 v[48:49], v[50:51], 0, v[90:91]
	global_store_dword v[48:49], v39, off nt
	v_lshl_add_u64 v[48:49], v[50:51], 0, v[92:93]
	global_store_dword v[48:49], v40, off nt
	v_lshl_add_u64 v[48:49], v[50:51], 0, v[94:95]
	global_store_dword v[48:49], v41, off nt
	v_lshl_add_u64 v[48:49], v[50:51], 0, v[96:97]
	global_store_dword v[48:49], v42, off nt
	v_lshl_add_u64 v[48:49], v[50:51], 0, v[98:99]
	global_store_dword v[48:49], v43, off nt
	v_lshl_add_u64 v[48:49], v[50:51], 0, v[100:101]
	global_store_dword v[48:49], v44, off nt
	v_lshl_add_u64 v[48:49], v[50:51], 0, v[102:103]
	global_store_dword v[48:49], v45, off nt
	v_lshl_add_u64 v[48:49], v[50:51], 0, v[104:105]
	global_store_dword v[48:49], v46, off nt
	v_lshl_add_u64 v[48:49], v[50:51], 0, v[106:107]
	global_store_dword v[48:49], v47, off nt
	v_mov_b32_e32 v49, v109
	s_cbranch_vccnz .LBB0_272
	v_mov_b32_e32 v113, 0x800
	s_mov_b64 s[34:35], 0x1489e000
	s_mov_b64 s[2:3], 0x1080
	s_mov_b64 s[0:1], 0x19800000
	v_mov_b32_e32 v49, v111
; __device__ __forceinline__ unsigned pk2(float lo, float hi) { f32v2_t v = {lo, hi}; bf16v2_t r = __builtin_convertvector(v, bf16v2_t); return __builtin_bit_cast(unsigned, r); }
; __device__ __forceinline__ int accrow(int reg, int hh) { return (reg & 3) + 8 * (reg >> 2) + 4 * hh; }
; __device__ __forceinline__ void vt_store(bf16_t* vt_row, int key32, const f32x16& a, int hh) {
; #pragma unroll
;   for (int g = 0; g < 4; ++g) {
;     const int pos = key32 + (g >> 1) * 16 + hh * 8 + (g & 1) * 4;
;     u32x2 w; w.x = pk2(a[4 * g], a[4 * g + 1]); w.y = pk2(a[4 * g + 2], a[4 * g + 3]);
;     *(u32x2*)(vt_row + pos) = w;
;   }
; }
; __device__ void phase_inproj(const Params& p, char* lds) {
;     ...
;           const int mb = m0 + wr * 64 + i * 32; const int nn = n0 - 2048 + wc * 64 + j * 32 + l31;
;           float* o = (samp ? p.out + O_VS + (size_t)(mb - TP) * 1024 : p.out + O_VP + (size_t)mb * 1024) + nn;
; #pragma unroll
;           for (int r = 0; r < 16; ++r) o[(size_t)accrow(r, hh) * 1024] = acc[i][j][r];
;           bf16_t* vt; int key32;
;           if (!samp) { const int b = mb >> 12; vt = (bf16_t*)(ws + W_D2) + ((size_t)(b * 1024 + nn)) * SEQP; key32 = mb & 4095; }
;           else { const int ts = mb - TP; const int b = ts >> 6; vt = (bf16_t*)(ws + W_D2 + SZ_VTP) + ((size_t)(b * 1024 + nn)) * LKS; key32 = PAST + (ts & 63); }
;           vt_store(vt, key32, acc[i][j], hh);
.LBB0_272:
	s_add_u32 s34, s96, s34
	v_or_b32_e32 v48, 32, v116
	s_addc_u32 s35, s97, s35
	v_or_b32_e32 v49, v49, v48
	v_mov_b64_e32 v[50:51], s[34:35]
	v_mad_i64_i32 v[50:51], s[2:3], s2, v49, v[50:51]
	v_or_b32_e32 v49, v113, v186
	v_cvt_pk_bf16_f32 v32, v32, v33
	v_cvt_pk_bf16_f32 v33, v34, v35
	v_lshlrev_b32_e32 v34, 1, v49
	v_mov_b32_e32 v35, v65
	s_movk_i32 s2, 0xfe0
	v_lshl_add_u64 v[50:51], v[50:51], 0, v[34:35]
	v_cvt_pk_bf16_f32 v34, v36, v37
	v_bitop3_b32 v36, v118, s2, 32 bitop3:0xc8
	v_readlane_b32 s2, v248, 0
	v_readlane_b32 s3, v248, 1
	s_load_dwordx4 s[44:47], s[2:3], 0xc0
	v_cvt_pk_bf16_f32 v35, v38, v39
	global_store_dwordx4 v[50:51], v[32:35], off
	s_mov_b64 s[2:3], 0x1079e000
	s_mov_b64 s[34:35], 0x10200000
	v_cvt_pk_bf16_f32 v32, v40, v41
	v_cvt_pk_bf16_f32 v33, v42, v43
	v_cvt_pk_bf16_f32 v34, v44, v45
	v_cvt_pk_bf16_f32 v35, v46, v47
	global_store_dwordx4 v[50:51], v[32:35], off offset:32
	s_waitcnt lgkmcnt(0)
	s_add_u32 s0, s46, s0
	s_addc_u32 s1, s47, s1
	v_or_b32_e32 v32, 32, v118
	v_ashrrev_i32_e32 v33, 31, v32
	v_lshlrev_b64 v[34:35], 12, v[118:119]
	v_lshlrev_b64 v[32:33], 12, v[32:33]
	v_lshl_add_u64 v[34:35], v[34:35], 0, s[28:29]
	v_cndmask_b32_e64 v39, v33, v35, s[38:39]
	v_cndmask_b32_e64 v38, v32, v34, s[38:39]
	v_lshl_add_u64 v[38:39], s[0:1], 0, v[38:39]
	v_lshl_add_u64 v[38:39], v[116:117], 2, v[38:39]
	v_lshl_add_u64 v[40:41], v[38:39], 0, v[76:77]
	global_store_dword v[40:41], v16, off nt
	v_lshl_add_u64 v[40:41], v[38:39], 0, v[78:79]
	global_store_dword v[40:41], v17, off nt
	v_lshl_add_u64 v[40:41], v[38:39], 0, v[80:81]
	global_store_dword v[40:41], v18, off nt
	v_lshl_add_u64 v[40:41], v[38:39], 0, v[82:83]
	global_store_dword v[40:41], v19, off nt
	v_lshl_add_u64 v[40:41], v[38:39], 0, v[84:85]
	global_store_dword v[40:41], v20, off nt
	v_lshl_add_u64 v[40:41], v[38:39], 0, v[86:87]
	global_store_dword v[40:41], v21, off nt
	v_lshl_add_u64 v[40:41], v[38:39], 0, v[88:89]
	global_store_dword v[40:41], v22, off nt
	v_lshl_add_u64 v[40:41], v[38:39], 0, v[90:91]
	global_store_dword v[40:41], v23, off nt
	v_lshl_add_u64 v[40:41], v[38:39], 0, v[92:93]
	global_store_dword v[40:41], v24, off nt
	v_lshl_add_u64 v[40:41], v[38:39], 0, v[94:95]
	global_store_dword v[40:41], v25, off nt
	v_lshl_add_u64 v[40:41], v[38:39], 0, v[96:97]
	global_store_dword v[40:41], v26, off nt
	v_lshl_add_u64 v[40:41], v[38:39], 0, v[98:99]
	global_store_dword v[40:41], v27, off nt
	v_lshl_add_u64 v[40:41], v[38:39], 0, v[100:101]
	global_store_dword v[40:41], v28, off nt
	v_lshl_add_u64 v[40:41], v[38:39], 0, v[102:103]
	global_store_dword v[40:41], v29, off nt
	v_lshl_add_u64 v[40:41], v[38:39], 0, v[104:105]
	v_lshl_add_u64 v[38:39], v[38:39], 0, v[106:107]
	global_store_dword v[38:39], v31, off nt
	s_mov_b64 s[0:1], 0x2080
	s_and_b64 vcc, exec, s[40:41]
	v_mov_b32_e32 v38, v109
	s_mov_b64 s[38:39], 0x2080
	s_mov_b64 s[42:43], 0x1079e000
	v_mov_b32_e32 v37, v36
	global_store_dword v[40:41], v30, off nt
	s_cbranch_vccnz .LBB0_274
	v_mov_b32_e32 v37, 0x820
	s_mov_b64 s[42:43], 0x1489e000
	s_mov_b64 s[38:39], 0x1080
	s_mov_b64 s[34:35], 0x19800000
	v_mov_b64_e32 v[32:33], v[34:35]
	v_mov_b32_e32 v38, v111
.LBB0_274:
	s_add_u32 s42, s96, s42
	s_addc_u32 s43, s97, s43
	v_or_b32_e32 v38, v38, v116
	v_mov_b64_e32 v[34:35], s[42:43]
	v_mad_i64_i32 v[34:35], s[38:39], s38, v38, v[34:35]
	v_readlane_b32 s38, v248, 0
	v_readlane_b32 s39, v248, 1
	s_load_dwordx4 s[44:47], s[38:39], 0xc0
	v_or_b32_e32 v37, v37, v186
	v_cvt_pk_bf16_f32 v16, v16, v17
	v_cvt_pk_bf16_f32 v17, v18, v19
	v_lshlrev_b32_e32 v18, 1, v37
	v_mov_b32_e32 v19, v65
	v_lshl_add_u64 v[34:35], v[34:35], 0, v[18:19]
	v_cvt_pk_bf16_f32 v18, v20, v21
	v_cvt_pk_bf16_f32 v19, v22, v23
	s_waitcnt lgkmcnt(0)
	s_add_u32 s34, s46, s34
	global_store_dwordx4 v[34:35], v[16:19], off
	s_addc_u32 s35, s47, s35
	s_and_b64 vcc, exec, s[40:41]
	v_cvt_pk_bf16_f32 v16, v24, v25
	v_cvt_pk_bf16_f32 v17, v26, v27
	v_cvt_pk_bf16_f32 v18, v28, v29
	v_cvt_pk_bf16_f32 v19, v30, v31
	global_store_dwordx4 v[34:35], v[16:19], off offset:32
	s_nop 1
	v_lshl_add_u64 v[16:17], s[34:35], 0, v[32:33]
	v_lshl_add_u64 v[16:17], v[116:117], 2, v[16:17]
	v_lshl_add_u64 v[18:19], v[16:17], 0, s[30:31]
	v_lshl_add_u64 v[16:17], v[16:17], 0, v[76:77]
	global_store_dword v[16:17], v0, off offset:128 nt
	v_lshl_add_u64 v[16:17], v[18:19], 0, v[78:79]
	global_store_dword v[16:17], v1, off nt
	v_lshl_add_u64 v[16:17], v[18:19], 0, v[80:81]
	global_store_dword v[16:17], v2, off nt
	v_lshl_add_u64 v[16:17], v[18:19], 0, v[82:83]
	global_store_dword v[16:17], v3, off nt
	v_lshl_add_u64 v[16:17], v[18:19], 0, v[84:85]
	global_store_dword v[16:17], v4, off nt
	v_lshl_add_u64 v[16:17], v[18:19], 0, v[86:87]
	global_store_dword v[16:17], v5, off nt
	v_lshl_add_u64 v[16:17], v[18:19], 0, v[88:89]
	global_store_dword v[16:17], v6, off nt
	v_lshl_add_u64 v[16:17], v[18:19], 0, v[90:91]
	global_store_dword v[16:17], v7, off nt
	v_lshl_add_u64 v[16:17], v[18:19], 0, v[92:93]
	global_store_dword v[16:17], v8, off nt
	v_lshl_add_u64 v[16:17], v[18:19], 0, v[94:95]
	global_store_dword v[16:17], v9, off nt
	v_lshl_add_u64 v[16:17], v[18:19], 0, v[96:97]
	global_store_dword v[16:17], v10, off nt
	v_lshl_add_u64 v[16:17], v[18:19], 0, v[98:99]
	global_store_dword v[16:17], v11, off nt
	v_lshl_add_u64 v[16:17], v[18:19], 0, v[100:101]
	global_store_dword v[16:17], v12, off nt
	v_lshl_add_u64 v[16:17], v[18:19], 0, v[102:103]
	global_store_dword v[16:17], v13, off nt
	v_lshl_add_u64 v[16:17], v[18:19], 0, v[104:105]
	global_store_dword v[16:17], v14, off nt
	v_lshl_add_u64 v[16:17], v[18:19], 0, v[106:107]
	global_store_dword v[16:17], v15, off nt
	s_cbranch_vccnz .LBB0_276
	v_mov_b32_e32 v36, 0x820
	s_mov_b64 s[2:3], 0x1489e000
	s_mov_b64 s[0:1], 0x1080
	v_mov_b32_e32 v109, v111
